# hand-written tr_item loop in P0 weight conversion: 16 loads in flight instead of serialized load-wait chain
# baseline (speedup 1.0000x reference)
; #define LAS __attribute__((address_space(3)))
; __global__ void __launch_bounds__(NTHR, 2) hybrid_fwd(Args args) {
;     extern __shared__ __attribute__((aligned(16))) unsigned char lds_raw[];
;     cg::grid_group grid = cg::this_grid();
;     LAS unsigned char* lds = (LAS unsigned char*)lds_raw;
;     int tid = threadIdx.x, lane = tid & 63, wave = __builtin_amdgcn_readfirstlane(tid >> 6);
;     int G = gridDim.x, bx = blockIdx.x;
;     int vcu = (G % 8 == 0) ? (bx % 8) * (G / 8) + bx / 8 : bx;
;     int gw = vcu * NWAVES + wave; int NGW = G * NWAVES;
;     PtrTab TB = (PtrTab)(lds + TAB_OFF);
;     if (tid == 0) {
; #pragma unroll
;         for (int i = 0; i < 31; ++i) TB[i] = (unsigned long long)args.in[i];
;     }
;     if (tid == 1) { TB[40] = 0ull; }
;     __syncthreads();
;     (void)xcd_barrier_post((unsigned*)(args.ws + WS_BAR), (volatile LAS unsigned*)(lds + TAB_OFF + 320));
_Z10hybrid_fwd4Args:
	s_mov_b64 s[100:101], s[0:1]
	s_load_dwordx2 s[4:5], s[0:1], 0x110
	s_load_dword s11, s[0:1], 0x118
	s_mov_b32 s12, s2
	s_add_u32 s2, s0, 0x110
	s_addc_u32 s3, s1, 0
	s_waitcnt lgkmcnt(0)
	s_mov_b32 s68, s4
	v_writelane_b32 v254, s4, 0
	v_and_b32_e32 v197, 0x3ff, v0
	s_nop 0
	v_writelane_b32 v254, s5, 1
	s_and_b32 s4, s4, 7
	v_readfirstlane_b32 s10, v197
	s_cmp_lg_u32 s4, 0
	v_writelane_b32 v254, s12, 2
	s_cbranch_scc1 .LBB0_1
	s_getpc_b64 s[98:99]

; #define LAS __attribute__((address_space(3)))
; #define g1 (tab_in(TB, 2) + l * D)
; __device__ __forceinline__ void tr_item(const float* W, int ldn, int col0, int k0, const float* g, bf16* WT, int ldk, int drow0, LAS float* scr, int lane) {
;     const int n4 = (lane & 15) * 4, kr = lane >> 4;
; #pragma unroll
;     for (int i = 0; i < 16; ++i) { const int kk = 4 * i + kr; f32x4 v = *(const f32x4*)(W + (size_t)(k0 + kk) * ldn + col0 + n4); if (g) v = v * g[k0 + kk];
;         LAS float* d = scr + kk * 65 + n4; d[0] = v.x; d[1] = v.y; d[2] = v.z; d[3] = v.w; }
;     LDS_WAIT(); asm volatile("" ::: "memory");
;     const int c = lane & 7;
; #pragma unroll
;     for (int j = 0; j < 8; ++j) { const int n = (lane >> 3) + 8 * j; const LAS float* s = scr + (8 * c) * 65 + n;
; __device__ __forceinline__ void phase_prologue(PtrTab TB, unsigned char* ws, float* xout, int l, LAS unsigned char* lds, int gw, int NGW, int lane, int wave) {
;     ...
;     constexpr int I_FI = 16 * 88, I_FO = 44 * 16, I_WIN = 16 * 64, I_WG = 16 * 48, I_UB = 16 * 16, I_UC = 8 * 16, I_RG = 32, I_SQ = 16 * 16, I_KV = 16 * 32;
;     constexpr int S0 = 0, S1 = S0 + I_FI, S2 = S1 + I_FO, S3 = S2 + I_WIN, S4 = S3 + I_WG, S5 = S4 + I_UB, S6 = S5 + I_UC, S7 = S6 + I_RG, S8 = S7 + I_RG, S9 = S8 + I_SQ, S10 = S9 + I_SQ,
;                   S11 = S10 + I_KV, S12 = S11 + I_SQ, S13 = S12 + I_FI, S14 = S13 + I_FO;
;     for (int it = gw; it < S14; it += NGW) {
;         if (it < S1 || (it >= S12 && it < S13)) {
;             const bool second = it >= S12; const int r = second ? it - S12 : it; const int kb = r / 88, nb = r % 88; const int n = nb * 64;
;             const int half = n >= DFF ? 1 : 0, nn = n - half * DFF; const int drow = (nn >> 7) * 256 + half * 128 + (nn & 127);
;             tr_item(second ? w2i : w1i, 2 * DFF, n, kb * 64, second ? g2 : g1, (bf16*)(ws + (second ? WS_W2IN : WS_W1IN)), D, drow, scr, lane);
;         } else if (it < S2 || it >= S13) {
;             const bool second = it >= S13; const int r = second ? it - S13 : it - S1; const int kb = r / 16, nb = r % 16;
;             tr_item(second ? w2o : w1o, D, nb * 64, kb * 64, nullptr, (bf16*)(ws + (second ? WS_W2OUT : WS_W1OUT)), DFF, nb * 64, scr, lane);
;         } else if (it < S3) { const int r = it - S2, kb = r / 64, nb = r % 64; tr_item(win, INW, nb * 64, kb * 64, gm, (bf16*)(ws + WS_WIN), D, nb * 64, scr, lane);
.LBB0_20:
	s_mul_i32 s0, s2, 0x4100
	v_lshlrev_b32_e32 v0, 2, v52
	s_add_i32 s2, s0, 0
	v_and_b32_e32 v8, 60, v0
	v_lshrrev_b32_e32 v10, 4, v52
	v_mov_b32_e32 v0, 0x410
	s_movk_i32 s0, 0x104
	v_mad_u32_u24 v35, v10, s0, v0
	v_mov_b32_e32 v0, 0x820
	v_mad_u32_u24 v37, v10, s0, v0
	v_mov_b32_e32 v0, 0xc30
	v_mad_u32_u24 v39, v10, s0, v0
	v_mov_b32_e32 v0, 0x1040
	v_mad_u32_u24 v41, v10, s0, v0
	v_lshlrev_b32_e32 v0, 3, v52
	v_and_b32_e32 v12, 56, v0
	v_lshlrev_b32_e32 v0, 1, v12
	v_mov_b32_e32 v1, v65
	v_mad_u32_u24 v43, v10, s0, v241
	v_mad_u32_u24 v45, v10, s0, v229
	v_mad_u32_u24 v47, v10, s0, v234
	v_mad_u32_u24 v49, v10, s0, v235
	v_mad_u32_u24 v51, v10, s0, v236
	v_mad_u32_u24 v54, v10, s0, v237
	v_mad_u32_u24 v56, v10, s0, v238
	v_lshl_add_u64 v[0:1], s[82:83], 0, v[0:1]
	s_mov_b64 s[0:1], 0x3300000
	s_mov_b64 s[6:7], 0x2a00000
	v_lshl_add_u64 v[14:15], v[0:1], 0, s[0:1]
	s_mov_b64 s[0:1], 0x2f00000
	v_lshl_add_u64 v[22:23], v[0:1], 0, s[6:7]
	s_mov_b64 s[6:7], 0x2800000
	v_lshrrev_b32_e32 v61, 3, v52
	v_lshl_add_u64 v[16:17], v[0:1], 0, s[0:1]
	s_mov_b64 s[0:1], 0x2d00000
	v_lshl_add_u64 v[24:25], v[0:1], 0, s[6:7]
	s_mov_b64 s[6:7], 0x2100000
	v_mul_u32_u24_e32 v2, 0x104, v12
	v_lshlrev_b32_e32 v3, 2, v61
	v_lshl_add_u64 v[18:19], v[0:1], 0, s[0:1]
	s_mov_b64 s[0:1], 0x2b00000
	v_lshl_add_u64 v[26:27], v[0:1], 0, s[6:7]
	s_mov_b64 s[6:7], 0x1900000
	v_lshl_add_u32 v9, v8, 2, s2
	v_add3_u32 v62, s2, v2, v3
	s_lshl_b32 s34, s94, 21
	v_lshl_add_u64 v[20:21], v[0:1], 0, s[0:1]
	s_lshl_b32 s0, s94, 17
	s_mov_b32 s1, s35
	s_lshl_b32 s2, s94, 19
	s_mov_b32 s3, s35
	v_lshl_add_u64 v[28:29], v[0:1], 0, s[6:7]
	s_mul_i32 s6, s94, 0x2c0000
	s_mov_b32 s7, s35
	s_mul_i32 s16, s94, 0x580000
	s_mov_b32 s17, s35
	s_lshl_b32 s12, s94, 20
	s_mov_b32 s13, s35
	v_mul_u32_u24_e32 v13, 0x104, v10
	v_or_b32_e32 v34, 4, v10
	v_or_b32_e32 v36, 8, v10
	v_or_b32_e32 v38, 12, v10
	v_or_b32_e32 v40, 16, v10
	v_or_b32_e32 v42, 20, v10
	v_or_b32_e32 v44, 24, v10
	v_or_b32_e32 v46, 28, v10
	v_or_b32_e32 v48, 32, v10
	v_or_b32_e32 v50, 36, v10
	v_or_b32_e32 v53, 40, v10
	v_or_b32_e32 v55, 44, v10
	v_or_b32_e32 v57, 48, v10
	v_or_b32_e32 v58, 52, v10
	v_or_b32_e32 v59, 56, v10
	v_or_b32_e32 v60, 60, v10
	v_or_b32_e32 v63, 8, v61
	v_or_b32_e32 v66, 16, v61
	v_or_b32_e32 v67, 24, v61
	v_or_b32_e32 v68, 32, v61
	v_or_b32_e32 v69, 40, v61
	v_or_b32_e32 v70, 48, v61
	v_or_b32_e32 v71, 56, v61
	s_lshl_b32 s14, s94, 10
	s_mov_b32 s15, s35
	s_mov_b32 s5, s35
	v_mov_b32_e32 v11, v65
	s_lshl_b32 s9, s10, 2
	s_lshl_b32 s11, s8, 2
	s_lshl_b32 s62, s10, 1
	s_lshl_b32 s63, s8, 1
	s_lshl_b32 s64, s10, 6
	s_lshl_b32 s65, s8, 6
	s_lshl_b32 s69, s10, 5
	s_lshl_b32 s70, s8, 5
	s_lshl_b64 s[24:25], s[34:35], 2
	s_lshl_b64 s[72:73], s[0:1], 2
	s_lshl_b64 s[80:81], s[2:3], 2
	s_lshl_b64 s[60:61], s[6:7], 2
	s_lshl_b64 s[38:39], s[16:17], 2
	s_mov_b32 s71, s10
	s_branch .LBB0_23
.LBB0_22:
	s_add_i32 s71, s71, s8
	s_add_i32 s9, s9, s11
	s_add_i32 s62, s62, s63
	s_add_i32 s64, s64, s65
	s_add_i32 s69, s69, s70
	s_cmpk_gt_i32 s71, 0x1e3f
	s_cbranch_scc1 .LBB0_214
.LBB0_23:
	s_mov_b32 s0, s71
	s_cmpk_lt_u32 s0, 1408
	s_cbranch_scc1 .Ltr_seg0
	s_cmpk_lt_u32 s0, 2112
	s_cbranch_scc1 .Ltr_seg1
	s_cmpk_lt_u32 s0, 3136
	s_cbranch_scc1 .Ltr_seg2
	s_cmpk_lt_u32 s0, 3904
	s_cbranch_scc1 .Ltr_seg3
	s_cmpk_lt_u32 s0, 4160
	s_cbranch_scc1 .Ltr_seg4
	s_cmpk_lt_u32 s0, 4288
	s_cbranch_scc1 .Ltr_seg5
	s_cmpk_lt_u32 s0, 4320
	s_cbranch_scc1 .Ltr_seg6
	s_cmpk_lt_u32 s0, 4352
	s_cbranch_scc1 .Ltr_seg7
	s_cmpk_lt_u32 s0, 4608
	s_cbranch_scc1 .Ltr_seg8
	s_cmpk_lt_u32 s0, 4864
	s_cbranch_scc1 .Ltr_seg9
	s_cmpk_lt_u32 s0, 5376
	s_cbranch_scc1 .Ltr_seg10
	s_cmpk_lt_u32 s0, 5632
	s_cbranch_scc1 .Ltr_seg11
	s_cmpk_lt_u32 s0, 7040
	s_cbranch_scc1 .Ltr_seg12
	s_branch .Ltr_seg13
.Ltr_seg0:
	s_movk_i32 s1, 88
	s_mov_b32 s5, 745
	s_movk_i32 s6, 24
	s_mov_b32 s13, 0x1600000
	s_movk_i32 s18, 5632
	s_movk_i32 s20, 0
	s_movk_i32 s21, 16
	s_mov_b32 s23, 0x800000
	s_movk_i32 s32, 1024
	s_movk_i32 s34, 5
	s_branch .Ltr_common
.Ltr_seg1:
	s_sub_u32 s0, s0, 1408
	s_movk_i32 s1, 16
	s_mov_b32 s5, 4097
	s_movk_i32 s6, 32
	s_mov_b32 s13, 0xb00000
	s_movk_i32 s18, 1024
	s_movk_i32 s20, 0
	s_movk_i32 s21, 0
	s_mov_b32 s23, 0x1300000
	s_movk_i32 s32, 2816
	s_movk_i32 s34, 0
	s_branch .Ltr_common
.Ltr_seg2:
	s_sub_u32 s0, s0, 2112
	s_movk_i32 s1, 64
	s_mov_b32 s5, 1025
	s_movk_i32 s6, 48
	s_mov_b32 s13, 0x1c08000
	s_movk_i32 s18, 7176
	s_movk_i32 s20, 0
	s_movk_i32 s21, 40
	s_mov_b32 s23, 0x1900000
	s_movk_i32 s32, 1024
	s_movk_i32 s34, 4
	s_branch .Ltr_common
.Ltr_seg3:
	s_sub_u32 s0, s0, 3136
	s_movk_i32 s1, 48
	s_mov_b32 s5, 1366
	s_movk_i32 s6, 48
	s_mov_b32 s13, 0x1c08000
	s_movk_i32 s18, 7176
	s_movk_i32 s20, 4104
	s_movk_i32 s21, 40
	s_mov_b32 s23, 0x2100000
	s_movk_i32 s32, 1024
	s_movk_i32 s34, 4
	s_branch .Ltr_common
.Ltr_seg4:
	s_sub_u32 s0, s0, 3904
	s_movk_i32 s1, 16
	s_mov_b32 s5, 4097
	s_movk_i32 s6, 152
	s_mov_b32 s13, 0x400000
	s_movk_i32 s18, 1024
	s_movk_i32 s20, 0
	s_movk_i32 s21, 0
	s_mov_b32 s23, 0x2800000
	s_movk_i32 s32, 1024
	s_movk_i32 s34, 0
	s_branch .Ltr_common
.Ltr_seg5:
	s_sub_u32 s0, s0, 4160
	s_movk_i32 s1, 16
	s_mov_b32 s5, 4097
	s_movk_i32 s6, 160
	s_mov_b32 s13, 0x200000
	s_movk_i32 s18, 1024
	s_movk_i32 s20, 0
	s_movk_i32 s21, 0
	s_mov_b32 s23, 0x2a00000
	s_movk_i32 s32, 512
	s_movk_i32 s34, 0
	s_branch .Ltr_common
.Ltr_seg6:
	s_sub_u32 s0, s0, 4288
	s_movk_i32 s1, 2
	s_mov_b32 s5, 32769
	s_movk_i32 s6, 112
	s_mov_b32 s13, 0x80000
	s_movk_i32 s18, 128
	s_movk_i32 s20, 0
	s_movk_i32 s21, 0
	s_mov_b32 s23, 0x140000
	s_movk_i32 s32, 128
	s_movk_i32 s34, 2
	s_branch .Ltr_common
; #define g1 (tab_in(TB, 2) + l * D)
; #define gm (tab_in(TB, 5) + l * D)
; __device__ __forceinline__ void phase_prologue(PtrTab TB, unsigned char* ws, float* xout, int l, LAS unsigned char* lds, int gw, int NGW, int lane, int wave) {
;     ...
;     for (int it = gw; it < S14; it += NGW) {
;         if (it < S1 || (it >= S12 && it < S13)) {
;             const bool second = it >= S12; const int r = second ? it - S12 : it; const int kb = r / 88, nb = r % 88; const int n = nb * 64;
;             const int half = n >= DFF ? 1 : 0, nn = n - half * DFF; const int drow = (nn >> 7) * 256 + half * 128 + (nn & 127);
;             tr_item(second ? w2i : w1i, 2 * DFF, n, kb * 64, second ? g2 : g1, (bf16*)(ws + (second ? WS_W2IN : WS_W1IN)), D, drow, scr, lane);
;         } else if (it < S2 || it >= S13) {
;             const bool second = it >= S13; const int r = second ? it - S13 : it - S1; const int kb = r / 16, nb = r % 16;
;             tr_item(second ? w2o : w1o, D, nb * 64, kb * 64, nullptr, (bf16*)(ws + (second ? WS_W2OUT : WS_W1OUT)), DFF, nb * 64, scr, lane);
;         } else if (it < S3) { const int r = it - S2, kb = r / 64, nb = r % 64; tr_item(win, INW, nb * 64, kb * 64, gm, (bf16*)(ws + WS_WIN), D, nb * 64, scr, lane);
;         } else if (it < S4) { const int r = it - S3, kb = r / 48, nb = r % 48; tr_item(win, INW, 4104 + nb * 64, kb * 64, gm, (bf16*)(ws + WS_WG), D, nb * 64, scr, lane);
;         } else if (it < S5) { const int r = it - S4, kb = r / 16, nb = r % 16; tr_item(wub, D, nb * 64, kb * 64, nullptr, (bf16*)(ws + WS_UB), D, nb * 64, scr, lane);
;         } else if (it < S6) { const int r = it - S5, kb = r / 16, nb = r % 16; tr_item(wuc, D, nb * 64, kb * 64, nullptr, (bf16*)(ws + WS_UC), 512, nb * 64, scr, lane);
;         } else if (it < S8) { const bool xg = it >= S7; const int r = xg ? it - S7 : it - S6; const int hh = r >> 2, kb = (r >> 1) & 1, nb = r & 1;
;             tr_item((xg ? wrx : wra) + hh * 16384, 128, nb * 64, kb * 64, nullptr, (bf16*)(ws + (xg ? WS_WXT : WS_WAT)) + hh * 16384, 128, nb * 64, scr, lane);
;         } else if (it < S9) { const int r = it - S8, kb = r / 16, nb = r % 16; tr_item(wo, D, nb * 64, kb * 64, nullptr, (bf16*)(ws + WS_WO), D, nb * 64, scr, lane);
;         } else if (it < S10) { const int r = it - S9, kb = r / 16, nb = r % 16; tr_item(wxq, D, nb * 64, kb * 64, gc, (bf16*)(ws + WS_WXQ), D, nb * 64, scr, lane);
.Ltr_seg7:
	s_sub_u32 s0, s0, 4320
	s_movk_i32 s1, 2
	s_mov_b32 s5, 32769
	s_movk_i32 s6, 128
	s_mov_b32 s13, 0x80000
	s_movk_i32 s18, 128
	s_movk_i32 s20, 0
	s_movk_i32 s21, 0
	s_mov_b32 s23, 0x180000
	s_movk_i32 s32, 128
	s_movk_i32 s34, 2
	s_branch .Ltr_common
.Ltr_seg8:
	s_sub_u32 s0, s0, 4352
	s_movk_i32 s1, 16
	s_mov_b32 s5, 4097
	s_movk_i32 s6, 168
	s_mov_b32 s13, 0x400000
	s_movk_i32 s18, 1024
	s_movk_i32 s20, 0
	s_movk_i32 s21, 0
	s_mov_b32 s23, 0x2b00000
	s_movk_i32 s32, 1024
	s_movk_i32 s34, 0
	s_branch .Ltr_common
.Ltr_seg9:
	s_sub_u32 s0, s0, 4608
	s_movk_i32 s1, 16
	s_mov_b32 s5, 4097
	s_movk_i32 s6, 192
	s_mov_b32 s13, 0x400000
	s_movk_i32 s18, 1024
	s_movk_i32 s20, 0
	s_movk_i32 s21, 176
	s_mov_b32 s23, 0x2d00000
	s_movk_i32 s32, 1024
	s_movk_i32 s34, 4
	s_branch .Ltr_common
.Ltr_seg10:
	s_sub_u32 s0, s0, 4864
	s_movk_i32 s1, 32
	s_mov_b32 s5, 2049
	s_movk_i32 s6, 200
	s_mov_b32 s13, 0x800000
	s_movk_i32 s18, 2048
	s_movk_i32 s20, 0
	s_movk_i32 s21, 0
	s_mov_b32 s23, 0x2f00000
	s_movk_i32 s32, 1024
	s_movk_i32 s34, 0
	s_branch .Ltr_common
.Ltr_seg11:
	s_sub_u32 s0, s0, 5376
	s_movk_i32 s1, 16
	s_mov_b32 s5, 4097
	s_movk_i32 s6, 208
	s_mov_b32 s13, 0x400000
	s_movk_i32 s18, 1024
	s_movk_i32 s20, 0
	s_movk_i32 s21, 0
	s_mov_b32 s23, 0x3300000
	s_movk_i32 s32, 1024
	s_movk_i32 s34, 0
	s_branch .Ltr_common
.Ltr_seg12:
	s_sub_u32 s0, s0, 5632
	s_movk_i32 s1, 88
	s_mov_b32 s5, 745
	s_movk_i32 s6, 224
	s_mov_b32 s13, 0x1600000
	s_movk_i32 s18, 5632
	s_movk_i32 s20, 0
	s_movk_i32 s21, 216
	s_mov_b32 s23, 0x3500000
	s_movk_i32 s32, 1024
	s_movk_i32 s34, 5
	s_branch .Ltr_common
.Ltr_seg13:
	s_sub_u32 s0, s0, 7040
	s_movk_i32 s1, 16
	s_mov_b32 s5, 4097
	s_movk_i32 s6, 232
	s_mov_b32 s13, 0xb00000
	s_movk_i32 s18, 1024
	s_movk_i32 s20, 0
	s_movk_i32 s21, 0
	s_mov_b32 s23, 0x4000000
	s_movk_i32 s32, 2816
	s_movk_i32 s34, 0
	s_branch .Ltr_common
.Ltr_common:
	s_load_dwordx2 s[60:61], s[100:101], s6
	s_mov_b64 s[72:73], 0
	s_bitcmp1_b32 s34, 2
	s_cbranch_scc0 .Ltr_nogptr
	s_load_dwordx2 s[72:73], s[100:101], s21
.Ltr_nogptr:
	s_mul_i32 s31, s0, s5
	s_lshr_b32 s31, s31, 16
	s_mul_i32 s87, s31, s1
	s_sub_u32 s87, s0, s87
	s_lshl_b32 s14, s31, 6
	s_lshl_b32 s15, s87, 6
	s_add_u32 s20, s20, s15
	s_bitcmp1_b32 s34, 0
	s_cbranch_scc0 .Ltr_noswi
	s_cmp_ge_u32 s87, 44
	s_cselect_b32 s24, 1, 0
	s_mul_i32 s25, s24, 44
	s_sub_u32 s25, s87, s25
	s_lshr_b32 s15, s25, 1
	s_lshl_b32 s15, s15, 8
	s_lshl_b32 s24, s24, 7
	s_add_u32 s15, s15, s24
	s_and_b32 s25, s25, 1
	s_lshl_b32 s25, s25, 6
	s_add_u32 s15, s15, s25
.Ltr_noswi:
	s_bitcmp1_b32 s34, 1
	s_cbranch_scc0 .Ltr_norg
	s_lshr_b32 s24, s0, 2
	s_mul_i32 s24, s24, 32512
	s_add_u32 s23, s23, s24
.Ltr_norg:
	s_mul_i32 s95, s94, s13
	s_mul_i32 s97, s14, s18
	s_add_u32 s97, s97, s20
	s_lshl_b32 s97, s97, 2
	s_add_u32 s95, s95, s97
	s_lshl_b32 s38, s18, 4
	s_lshl_b32 s44, s32, 4
	s_mul_i32 s24, s15, s32
	s_add_u32 s24, s24, s14
	s_lshl_b32 s24, s24, 1
	s_add_u32 s24, s24, s23
	s_add_u32 s24, s82, s24
	s_addc_u32 s25, s83, 0
	s_lshl_b32 s97, s94, 12
	s_lshl_b32 s1, s14, 2
	s_add_u32 s97, s97, s1
	v_mul_u32_u24_e32 v232, s18, v10
	v_add_lshl_u32 v232, v232, v8, 2
	v_lshlrev_b32_e32 v233, 2, v10
	v_mul_u32_u24_e32 v244, s32, v61
	v_add_lshl_u32 v244, v244, v12, 1
	v_add_u32_e32 v245, s44, v244
	v_add_u32_e32 v246, s44, v245
	v_add_u32_e32 v247, s44, v246
	v_add_u32_e32 v248, s44, v247
	v_add_u32_e32 v249, s44, v248
	v_add_u32_e32 v250, s44, v249
	v_add_u32_e32 v251, s44, v250
	v_add_u32_e32 v242, v9, v13
	v_add_u32_e32 v243, 0x400, v62
	s_waitcnt lgkmcnt(0)
	s_add_u32 s2, s60, s95
	s_addc_u32 s3, s61, 0
	s_add_u32 s98, s72, s97
	s_addc_u32 s99, s73, 0
	s_bitcmp1_b32 s34, 2
	s_cbranch_scc0 .Ltr_gone
	global_load_dword v210, v233, s[98:99] offset:0
	global_load_dword v211, v233, s[98:99] offset:16
	global_load_dword v212, v233, s[98:99] offset:32
	global_load_dword v213, v233, s[98:99] offset:48
	global_load_dword v214, v233, s[98:99] offset:64
	global_load_dword v215, v233, s[98:99] offset:80
	global_load_dword v216, v233, s[98:99] offset:96
	global_load_dword v217, v233, s[98:99] offset:112
	global_load_dword v218, v233, s[98:99] offset:128
	global_load_dword v219, v233, s[98:99] offset:144
	global_load_dword v220, v233, s[98:99] offset:160
	global_load_dword v221, v233, s[98:99] offset:176
	global_load_dword v222, v233, s[98:99] offset:192
	global_load_dword v223, v233, s[98:99] offset:208
	global_load_dword v230, v233, s[98:99] offset:224
	global_load_dword v231, v233, s[98:99] offset:240
	s_branch .Ltr_gdone
.Ltr_gone:
	v_mov_b32_e32 v210, 1.0
	v_mov_b32_e32 v211, 1.0
	v_mov_b32_e32 v212, 1.0
	v_mov_b32_e32 v213, 1.0
	v_mov_b32_e32 v214, 1.0
	v_mov_b32_e32 v215, 1.0
	v_mov_b32_e32 v216, 1.0
	v_mov_b32_e32 v217, 1.0
	v_mov_b32_e32 v218, 1.0
	v_mov_b32_e32 v219, 1.0
	v_mov_b32_e32 v220, 1.0
	v_mov_b32_e32 v221, 1.0
	v_mov_b32_e32 v222, 1.0
	v_mov_b32_e32 v223, 1.0
	v_mov_b32_e32 v230, 1.0
	v_mov_b32_e32 v231, 1.0
; #define LAS __attribute__((address_space(3)))
; #define LDS_WAIT() asm volatile("s_waitcnt lgkmcnt(0)" ::: "memory")
; __device__ __forceinline__ void tr_item(const float* W, int ldn, int col0, int k0, const float* g, bf16* WT, int ldk, int drow0, LAS float* scr, int lane) {
;     const int n4 = (lane & 15) * 4, kr = lane >> 4;
; #pragma unroll
;     for (int i = 0; i < 16; ++i) { const int kk = 4 * i + kr; f32x4 v = *(const f32x4*)(W + (size_t)(k0 + kk) * ldn + col0 + n4); if (g) v = v * g[k0 + kk];
;         LAS float* d = scr + kk * 65 + n4; d[0] = v.x; d[1] = v.y; d[2] = v.z; d[3] = v.w; }
;     LDS_WAIT(); asm volatile("" ::: "memory");
.Ltr_gdone:
	global_load_dwordx4 v[146:149], v232, s[2:3]
	v_add_u32_e32 v232, s38, v232
	global_load_dwordx4 v[150:153], v232, s[2:3]
	v_add_u32_e32 v232, s38, v232
	global_load_dwordx4 v[154:157], v232, s[2:3]
	v_add_u32_e32 v232, s38, v232
	global_load_dwordx4 v[158:161], v232, s[2:3]
	v_add_u32_e32 v232, s38, v232
	global_load_dwordx4 v[162:165], v232, s[2:3]
	v_add_u32_e32 v232, s38, v232
	global_load_dwordx4 v[166:169], v232, s[2:3]
	v_add_u32_e32 v232, s38, v232
	global_load_dwordx4 v[170:173], v232, s[2:3]
	v_add_u32_e32 v232, s38, v232
	global_load_dwordx4 v[174:177], v232, s[2:3]
	v_add_u32_e32 v232, s38, v232
	global_load_dwordx4 v[178:181], v232, s[2:3]
	v_add_u32_e32 v232, s38, v232
	global_load_dwordx4 v[182:185], v232, s[2:3]
	v_add_u32_e32 v232, s38, v232
	global_load_dwordx4 v[186:189], v232, s[2:3]
	v_add_u32_e32 v232, s38, v232
	global_load_dwordx4 v[190:193], v232, s[2:3]
	v_add_u32_e32 v232, s38, v232
	global_load_dwordx4 v[114:117], v232, s[2:3]
	v_add_u32_e32 v232, s38, v232
	global_load_dwordx4 v[118:121], v232, s[2:3]
	v_add_u32_e32 v232, s38, v232
	global_load_dwordx4 v[122:125], v232, s[2:3]
	v_add_u32_e32 v232, s38, v232
	global_load_dwordx4 v[126:129], v232, s[2:3]
	s_waitcnt vmcnt(15)
	v_mul_f32_e32 v146, v210, v146
	v_mul_f32_e32 v147, v210, v147
	v_mul_f32_e32 v148, v210, v148
	v_mul_f32_e32 v149, v210, v149
	ds_write2_b32 v242, v146, v147 offset1:1
	ds_write2_b32 v242, v148, v149 offset0:2 offset1:3
	v_add_u32_e32 v242, 0x410, v242
	s_waitcnt vmcnt(14)
	v_mul_f32_e32 v150, v211, v150
	v_mul_f32_e32 v151, v211, v151
	v_mul_f32_e32 v152, v211, v152
	v_mul_f32_e32 v153, v211, v153
	ds_write2_b32 v242, v150, v151 offset1:1
	ds_write2_b32 v242, v152, v153 offset0:2 offset1:3
	v_add_u32_e32 v242, 0x410, v242
	s_waitcnt vmcnt(13)
	v_mul_f32_e32 v154, v212, v154
	v_mul_f32_e32 v155, v212, v155
	v_mul_f32_e32 v156, v212, v156
	v_mul_f32_e32 v157, v212, v157
	ds_write2_b32 v242, v154, v155 offset1:1
	ds_write2_b32 v242, v156, v157 offset0:2 offset1:3
	v_add_u32_e32 v242, 0x410, v242
	s_waitcnt vmcnt(12)
	v_mul_f32_e32 v158, v213, v158
	v_mul_f32_e32 v159, v213, v159
	v_mul_f32_e32 v160, v213, v160
	v_mul_f32_e32 v161, v213, v161
	ds_write2_b32 v242, v158, v159 offset1:1
	ds_write2_b32 v242, v160, v161 offset0:2 offset1:3
	v_add_u32_e32 v242, 0x410, v242
	s_waitcnt vmcnt(11)
	v_mul_f32_e32 v162, v214, v162
	v_mul_f32_e32 v163, v214, v163
	v_mul_f32_e32 v164, v214, v164
	v_mul_f32_e32 v165, v214, v165
	ds_write2_b32 v242, v162, v163 offset1:1
	ds_write2_b32 v242, v164, v165 offset0:2 offset1:3
	v_add_u32_e32 v242, 0x410, v242
	s_waitcnt vmcnt(10)
	v_mul_f32_e32 v166, v215, v166
	v_mul_f32_e32 v167, v215, v167
	v_mul_f32_e32 v168, v215, v168
	v_mul_f32_e32 v169, v215, v169
	ds_write2_b32 v242, v166, v167 offset1:1
	ds_write2_b32 v242, v168, v169 offset0:2 offset1:3
	v_add_u32_e32 v242, 0x410, v242
	s_waitcnt vmcnt(9)
	v_mul_f32_e32 v170, v216, v170
	v_mul_f32_e32 v171, v216, v171
	v_mul_f32_e32 v172, v216, v172
	v_mul_f32_e32 v173, v216, v173
	ds_write2_b32 v242, v170, v171 offset1:1
	ds_write2_b32 v242, v172, v173 offset0:2 offset1:3
	v_add_u32_e32 v242, 0x410, v242
	s_waitcnt vmcnt(8)
	v_mul_f32_e32 v174, v217, v174
	v_mul_f32_e32 v175, v217, v175
	v_mul_f32_e32 v176, v217, v176
	v_mul_f32_e32 v177, v217, v177
	ds_write2_b32 v242, v174, v175 offset1:1
	ds_write2_b32 v242, v176, v177 offset0:2 offset1:3
	v_add_u32_e32 v242, 0x410, v242
	s_waitcnt vmcnt(7)
	v_mul_f32_e32 v178, v218, v178
	v_mul_f32_e32 v179, v218, v179
	v_mul_f32_e32 v180, v218, v180
	v_mul_f32_e32 v181, v218, v181
	ds_write2_b32 v242, v178, v179 offset1:1
	ds_write2_b32 v242, v180, v181 offset0:2 offset1:3
	v_add_u32_e32 v242, 0x410, v242
	s_waitcnt vmcnt(6)
	v_mul_f32_e32 v182, v219, v182
	v_mul_f32_e32 v183, v219, v183
	v_mul_f32_e32 v184, v219, v184
	v_mul_f32_e32 v185, v219, v185
	ds_write2_b32 v242, v182, v183 offset1:1
	ds_write2_b32 v242, v184, v185 offset0:2 offset1:3
	v_add_u32_e32 v242, 0x410, v242
	s_waitcnt vmcnt(5)
	v_mul_f32_e32 v186, v220, v186
	v_mul_f32_e32 v187, v220, v187
	v_mul_f32_e32 v188, v220, v188
	v_mul_f32_e32 v189, v220, v189
	ds_write2_b32 v242, v186, v187 offset1:1
	ds_write2_b32 v242, v188, v189 offset0:2 offset1:3
	v_add_u32_e32 v242, 0x410, v242
	s_waitcnt vmcnt(4)
	v_mul_f32_e32 v190, v221, v190
	v_mul_f32_e32 v191, v221, v191
	v_mul_f32_e32 v192, v221, v192
	v_mul_f32_e32 v193, v221, v193
	ds_write2_b32 v242, v190, v191 offset1:1
	ds_write2_b32 v242, v192, v193 offset0:2 offset1:3
	v_add_u32_e32 v242, 0x410, v242
	s_waitcnt vmcnt(3)
; #define LAS __attribute__((address_space(3)))
; __device__ __forceinline__ unsigned pk2(float lo, float hi) { return f2bf(lo) | (f2bf(hi) << 16); }
; #define LDS_WAIT() asm volatile("s_waitcnt lgkmcnt(0)" ::: "memory")
; __device__ __forceinline__ void tr_item(const float* W, int ldn, int col0, int k0, const float* g, bf16* WT, int ldk, int drow0, LAS float* scr, int lane) {
;     ...
;     for (int i = 0; i < 16; ++i) { const int kk = 4 * i + kr; f32x4 v = *(const f32x4*)(W + (size_t)(k0 + kk) * ldn + col0 + n4); if (g) v = v * g[k0 + kk];
;         LAS float* d = scr + kk * 65 + n4; d[0] = v.x; d[1] = v.y; d[2] = v.z; d[3] = v.w; }
;     LDS_WAIT(); asm volatile("" ::: "memory");
;     const int c = lane & 7;
; #pragma unroll
;     for (int j = 0; j < 8; ++j) { const int n = (lane >> 3) + 8 * j; const LAS float* s = scr + (8 * c) * 65 + n;
;         v4u o; o.x = pk2(s[0 * 65], s[1 * 65]); o.y = pk2(s[2 * 65], s[3 * 65]); o.z = pk2(s[4 * 65], s[5 * 65]); o.w = pk2(s[6 * 65], s[7 * 65]);
;         *(v4u*)(WT + (size_t)(drow0 + n) * ldk + k0 + 8 * c) = o; }
;     LDS_WAIT(); asm volatile("" ::: "memory");
	v_mul_f32_e32 v114, v222, v114
	v_mul_f32_e32 v115, v222, v115
	v_mul_f32_e32 v116, v222, v116
	v_mul_f32_e32 v117, v222, v117
	ds_write2_b32 v242, v114, v115 offset1:1
	ds_write2_b32 v242, v116, v117 offset0:2 offset1:3
	v_add_u32_e32 v242, 0x410, v242
	s_waitcnt vmcnt(2)
	v_mul_f32_e32 v118, v223, v118
	v_mul_f32_e32 v119, v223, v119
	v_mul_f32_e32 v120, v223, v120
	v_mul_f32_e32 v121, v223, v121
	ds_write2_b32 v242, v118, v119 offset1:1
	ds_write2_b32 v242, v120, v121 offset0:2 offset1:3
	v_add_u32_e32 v242, 0x410, v242
	s_waitcnt vmcnt(1)
	v_mul_f32_e32 v122, v230, v122
	v_mul_f32_e32 v123, v230, v123
	v_mul_f32_e32 v124, v230, v124
	v_mul_f32_e32 v125, v230, v125
	ds_write2_b32 v242, v122, v123 offset1:1
	ds_write2_b32 v242, v124, v125 offset0:2 offset1:3
	v_add_u32_e32 v242, 0x410, v242
	s_waitcnt vmcnt(0)
	v_mul_f32_e32 v126, v231, v126
	v_mul_f32_e32 v127, v231, v127
	v_mul_f32_e32 v128, v231, v128
	v_mul_f32_e32 v129, v231, v129
	ds_write2_b32 v242, v126, v127 offset1:1
	ds_write2_b32 v242, v128, v129 offset0:2 offset1:3
	s_waitcnt lgkmcnt(0)
	ds_read2_b32 v[146:147], v62 offset0:0 offset1:65
	ds_read2_b32 v[148:149], v62 offset0:130 offset1:195
	ds_read2_b32 v[150:151], v243 offset0:4 offset1:69
	ds_read2_b32 v[152:153], v243 offset0:134 offset1:199
	ds_read2_b32 v[154:155], v62 offset0:8 offset1:73
	ds_read2_b32 v[156:157], v62 offset0:138 offset1:203
	ds_read2_b32 v[158:159], v243 offset0:12 offset1:77
	ds_read2_b32 v[160:161], v243 offset0:142 offset1:207
	ds_read2_b32 v[162:163], v62 offset0:16 offset1:81
	ds_read2_b32 v[164:165], v62 offset0:146 offset1:211
	ds_read2_b32 v[166:167], v243 offset0:20 offset1:85
	ds_read2_b32 v[168:169], v243 offset0:150 offset1:215
	s_waitcnt lgkmcnt(8)
	v_cvt_pk_bf16_f32 v146, v146, v147
	v_cvt_pk_bf16_f32 v147, v148, v149
	v_cvt_pk_bf16_f32 v148, v150, v151
	v_cvt_pk_bf16_f32 v149, v152, v153
	global_store_dwordx4 v244, v[146:149], s[24:25]
	ds_read2_b32 v[170:171], v62 offset0:24 offset1:89
	ds_read2_b32 v[172:173], v62 offset0:154 offset1:219
	ds_read2_b32 v[174:175], v243 offset0:28 offset1:93
	ds_read2_b32 v[176:177], v243 offset0:158 offset1:223
	s_waitcnt lgkmcnt(8)
	v_cvt_pk_bf16_f32 v154, v154, v155
	v_cvt_pk_bf16_f32 v155, v156, v157
	v_cvt_pk_bf16_f32 v156, v158, v159
	v_cvt_pk_bf16_f32 v157, v160, v161
	global_store_dwordx4 v245, v[154:157], s[24:25]
	ds_read2_b32 v[178:179], v62 offset0:32 offset1:97
	ds_read2_b32 v[180:181], v62 offset0:162 offset1:227
	ds_read2_b32 v[182:183], v243 offset0:36 offset1:101
	ds_read2_b32 v[184:185], v243 offset0:166 offset1:231
	s_waitcnt lgkmcnt(8)
	v_cvt_pk_bf16_f32 v162, v162, v163
	v_cvt_pk_bf16_f32 v163, v164, v165
	v_cvt_pk_bf16_f32 v164, v166, v167
	v_cvt_pk_bf16_f32 v165, v168, v169
	global_store_dwordx4 v246, v[162:165], s[24:25]
	ds_read2_b32 v[186:187], v62 offset0:40 offset1:105
	ds_read2_b32 v[188:189], v62 offset0:170 offset1:235
	ds_read2_b32 v[190:191], v243 offset0:44 offset1:109
	ds_read2_b32 v[192:193], v243 offset0:174 offset1:239
	s_waitcnt lgkmcnt(8)
	v_cvt_pk_bf16_f32 v170, v170, v171
	v_cvt_pk_bf16_f32 v171, v172, v173
	v_cvt_pk_bf16_f32 v172, v174, v175
	v_cvt_pk_bf16_f32 v173, v176, v177
	global_store_dwordx4 v247, v[170:173], s[24:25]
	ds_read2_b32 v[114:115], v62 offset0:48 offset1:113
	ds_read2_b32 v[116:117], v62 offset0:178 offset1:243
	ds_read2_b32 v[118:119], v243 offset0:52 offset1:117
	ds_read2_b32 v[120:121], v243 offset0:182 offset1:247
	s_waitcnt lgkmcnt(8)
	v_cvt_pk_bf16_f32 v178, v178, v179
	v_cvt_pk_bf16_f32 v179, v180, v181
	v_cvt_pk_bf16_f32 v180, v182, v183
	v_cvt_pk_bf16_f32 v181, v184, v185
	global_store_dwordx4 v248, v[178:181], s[24:25]
	ds_read2_b32 v[122:123], v62 offset0:56 offset1:121
	ds_read2_b32 v[124:125], v62 offset0:186 offset1:251
	ds_read2_b32 v[126:127], v243 offset0:60 offset1:125
	ds_read2_b32 v[128:129], v243 offset0:190 offset1:255
	s_waitcnt lgkmcnt(8)
	v_cvt_pk_bf16_f32 v186, v186, v187
	v_cvt_pk_bf16_f32 v187, v188, v189
	v_cvt_pk_bf16_f32 v188, v190, v191
	v_cvt_pk_bf16_f32 v189, v192, v193
	global_store_dwordx4 v249, v[186:189], s[24:25]
	s_waitcnt lgkmcnt(4)
	v_cvt_pk_bf16_f32 v114, v114, v115
	v_cvt_pk_bf16_f32 v115, v116, v117
	v_cvt_pk_bf16_f32 v116, v118, v119
	v_cvt_pk_bf16_f32 v117, v120, v121
	global_store_dwordx4 v250, v[114:117], s[24:25]
	s_waitcnt lgkmcnt(0)
	v_cvt_pk_bf16_f32 v122, v122, v123
	v_cvt_pk_bf16_f32 v123, v124, v125
	v_cvt_pk_bf16_f32 v124, v126, v127
	v_cvt_pk_bf16_f32 v125, v128, v129
	global_store_dwordx4 v251, v[122:125], s[24:25]
	s_branch .LBB0_22

; __global__ void __launch_bounds__(NTHR, 2) hybrid_fwd(Args args) {
;     extern __shared__ __attribute__((aligned(16))) unsigned char lds_raw[];
	.amdhsa_kernel _Z10hybrid_fwd4Args
		.amdhsa_group_segment_fixed_size 0
		.amdhsa_private_segment_fixed_size 0
		.amdhsa_kernarg_size 528
		.amdhsa_user_sgpr_count 2
		.amdhsa_user_sgpr_dispatch_ptr 0
		.amdhsa_user_sgpr_queue_ptr 0
		.amdhsa_user_sgpr_kernarg_segment_ptr 1
		.amdhsa_user_sgpr_dispatch_id 0
		.amdhsa_user_sgpr_kernarg_preload_length 0
		.amdhsa_user_sgpr_kernarg_preload_offset 0
		.amdhsa_user_sgpr_private_segment_size 0
		.amdhsa_uses_dynamic_stack 0
		.amdhsa_enable_private_segment 0
		.amdhsa_system_sgpr_workgroup_id_x 1
		.amdhsa_system_sgpr_workgroup_id_y 0
		.amdhsa_system_sgpr_workgroup_id_z 0
		.amdhsa_system_sgpr_workgroup_info 0
		.amdhsa_system_vgpr_workitem_id 2
		.amdhsa_next_free_vgpr 256
		.amdhsa_next_free_sgpr 102
		.amdhsa_accum_offset 256
		.amdhsa_reserve_vcc 1
		.amdhsa_float_round_mode_32 0
		.amdhsa_float_round_mode_16_64 0
		.amdhsa_float_denorm_mode_32 3
		.amdhsa_float_denorm_mode_16_64 3
		.amdhsa_dx10_clamp 1
		.amdhsa_ieee_mode 1
		.amdhsa_fp16_overflow 0
		.amdhsa_tg_split 0
		.amdhsa_exception_fp_ieee_invalid_op 0
		.amdhsa_exception_fp_denorm_src 0
		.amdhsa_exception_fp_ieee_div_zero 0
		.amdhsa_exception_fp_ieee_overflow 0
		.amdhsa_exception_fp_ieee_underflow 0
		.amdhsa_exception_fp_ieee_inexact 0
		.amdhsa_exception_int_div_zero 0
	.end_amdhsa_kernel

; __global__ void __launch_bounds__(NTHR, 2) hybrid_fwd(Args args) {
;     extern __shared__ __attribute__((aligned(16))) unsigned char lds_raw[];
amdhsa.kernels:
  - .agpr_count:     0
    .args:
      - .offset:         0
        .size:           272
        .value_kind:     by_value
      - .offset:         272
        .size:           4
        .value_kind:     hidden_block_count_x
      - .offset:         276
        .size:           4
        .value_kind:     hidden_block_count_y
      - .offset:         280
        .size:           4
        .value_kind:     hidden_block_count_z
      - .offset:         284
        .size:           2
        .value_kind:     hidden_group_size_x
      - .offset:         286
        .size:           2
        .value_kind:     hidden_group_size_y
      - .offset:         288
        .size:           2
        .value_kind:     hidden_group_size_z
      - .offset:         290
        .size:           2
        .value_kind:     hidden_remainder_x
      - .offset:         292
        .size:           2
        .value_kind:     hidden_remainder_y
      - .offset:         294
        .size:           2
        .value_kind:     hidden_remainder_z
      - .offset:         312
        .size:           8
        .value_kind:     hidden_global_offset_x
      - .offset:         320
        .size:           8
        .value_kind:     hidden_global_offset_y
      - .offset:         328
        .size:           8
        .value_kind:     hidden_global_offset_z
      - .offset:         336
        .size:           2
        .value_kind:     hidden_grid_dims
      - .offset:         360
        .size:           8
        .value_kind:     hidden_multigrid_sync_arg
      - .offset:         392
        .size:           4
        .value_kind:     hidden_dynamic_lds_size
    .group_segment_fixed_size: 0
    .kernarg_segment_align: 8
    .kernarg_segment_size: 528
    .language:       OpenCL C
    .language_version:
      - 2
      - 0
    .max_flat_workgroup_size: 512
    .name:           _Z10hybrid_fwd4Args
    .private_segment_fixed_size: 0
    .sgpr_count:     108
    .sgpr_spill_count: 90
    .symbol:         _Z10hybrid_fwd4Args.kd
    .uniform_work_group_size: 1
    .uses_dynamic_stack: false
    .vgpr_count:     256
    .vgpr_spill_count: 0
    .wavefront_size: 64
